# attention: second half's K fragments prefetched into the VGPRs freed by DMA staging right after the first half's QK MFMAs
# baseline (speedup 1.0000x reference)
; __device__ __forceinline__ void phase_attn(KP P, int l_, unsigned char* shm) {
;     ...
;                     const u16* Ks = (const u16*)(base + mp * KT_B) + hf * 64 * KROW;
;                     const u16* Vt = (const u16*)(base + 2 * KT_B) + hf * 64;
;                     f32x4 st[4];
;                     bf16x8 kfr[4][2];
; #pragma unroll
;                     for (int kt = 0; kt < 4; ++kt)
; #pragma unroll
;                         for (int ks = 0; ks < 2; ++ks) kfr[kt][ks] = *(const bf16x8*)(Ks + (kt * 16 + l15) * KROW + ks * 32 + g * 8);
;                     uint2 vfa[8][2], vfb[8][2];
; #pragma unroll
;                     for (int e = 0; e < 8; ++e)
; #pragma unroll
;                         for (int k2 = 0; k2 < 2; ++k2) { const u16* vp = Vt + (e * 16 + l15) * VROW + k2 * 32 + g * 4; vfa[e][k2] = *(const uint2*)vp; vfb[e][k2] = *(const uint2*)(vp + 16); }
;                     __builtin_amdgcn_sched_barrier(0);
; #pragma unroll
;                     for (int kt = 0; kt < 4; ++kt) { st[kt] = (f32x4){0.f, 0.f, 0.f, 0.f};
; #pragma unroll
;                         for (int ks = 0; ks < 2; ++ks) st[kt] = __builtin_amdgcn_mfma_f32_16x16x32_bf16(kfr[kt][ks], qf[ks], st[kt], 0, 0, 0); }
;                     if (kb == qb) {
;                         asm volatile("" ::: "memory");
;                         const int qr = rq * 16 + l15;
; #pragma unroll
;                         for (int kt = 0; kt < 4; ++kt)
; #pragma unroll
;                             for (int jj = 0; jj < 4; ++jj) if (kt * 16 + g * 4 + jj > qr) st[kt][jj] = -INFINITY;
.LBB0_2656:
	ds_read_b128 v[138:141], v208
	ds_read_b128 v[142:145], v209
	ds_read_b128 v[146:149], v208 offset:2048
	ds_read_b128 v[212:215], v209 offset:2048
	ds_read_b128 v[216:219], v208 offset:4096
	ds_read_b128 v[220:223], v209 offset:4096
	ds_read_b128 v[224:227], v208 offset:6144
	ds_read_b128 v[242:245], v209 offset:6144
	ds_read_b128 v[134:137], v207
	ds_read_b128 v[130:133], v206
	ds_read_b128 v[126:129], v207 offset:4096
	ds_read_b128 v[122:125], v206 offset:4096
	ds_read_b128 v[118:121], v207 offset:8192
	ds_read_b128 v[114:117], v206 offset:8192
	ds_read_b128 v[110:113], v207 offset:12288
	ds_read_b128 v[106:109], v206 offset:12288
	ds_read_b128 v[102:105], v207 offset:16384
	ds_read_b128 v[98:101], v206 offset:16384
	ds_read_b128 v[94:97], v207 offset:20480
	ds_read_b128 v[90:93], v206 offset:20480
	ds_read_b128 v[86:89], v207 offset:24576
	ds_read_b128 v[82:85], v206 offset:24576
	ds_read_b128 v[78:81], v207 offset:28672
	ds_read_b128 v[74:77], v206 offset:28672
	s_waitcnt lgkmcnt(14)
	v_mfma_f32_16x16x32_bf16 v[138:141], v[138:141], v[18:21], v[248:251]
	s_cmp_lg_u32 s58, s52
	v_mfma_f32_16x16x32_bf16 v[150:153], v[142:145], v[22:25], v[138:141]
	v_mfma_f32_16x16x32_bf16 v[138:141], v[146:149], v[18:21], v[248:251]
	v_mfma_f32_16x16x32_bf16 v[146:149], v[212:215], v[22:25], v[138:141]
	v_mfma_f32_16x16x32_bf16 v[138:141], v[216:219], v[18:21], v[248:251]
	v_mfma_f32_16x16x32_bf16 v[142:145], v[224:227], v[18:21], v[248:251]
	v_mfma_f32_16x16x32_bf16 v[138:141], v[220:223], v[22:25], v[138:141]
	v_mfma_f32_16x16x32_bf16 v[142:145], v[242:245], v[22:25], v[142:145]
	ds_read_b128 v[0:3], v208 offset:8192
	ds_read_b128 v[6:9], v209 offset:8192
	ds_read_b128 v[10:13], v208 offset:10240
	ds_read_b128 v[14:17], v209 offset:10240
	ds_read_b128 v[26:29], v208 offset:12288
	ds_read_b128 v[30:33], v209 offset:12288
	ds_read_b128 v[34:37], v208 offset:14336
	ds_read_b128 v[38:41], v209 offset:14336
	s_cbranch_scc1 .LBB0_2658
	s_nop 0
	v_cndmask_b32_e64 v186, v150, v241, s[8:9]
	v_cndmask_b32_e64 v150, v186, v150, s[10:11]
	v_cndmask_b32_e64 v151, v241, v151, s[10:11]
	v_cndmask_b32_e64 v152, v152, v241, s[12:13]
	v_cndmask_b32_e64 v153, v153, v241, s[14:15]
	v_cndmask_b32_e64 v146, v146, v241, s[16:17]
	v_cndmask_b32_e64 v147, v147, v241, s[18:19]
	v_cndmask_b32_e64 v148, v148, v241, s[20:21]
	v_cndmask_b32_e64 v149, v149, v241, s[22:23]
	v_cndmask_b32_e64 v138, v138, v241, s[24:25]
	v_cndmask_b32_e64 v139, v139, v241, s[26:27]
	v_cndmask_b32_e64 v140, v140, v241, s[28:29]
	v_cndmask_b32_e64 v141, v141, v241, s[30:31]
	v_cndmask_b32_e64 v142, v142, v241, s[34:35]
	v_cndmask_b32_e64 v143, v143, v241, s[36:37]
	v_cndmask_b32_e64 v144, v144, v241, s[38:39]
	v_cndmask_b32_e64 v145, v145, v241, s[40:41]

; __device__ __forceinline__ void phase_attn(KP P, int l_, unsigned char* shm) {
;     ...
; #pragma unroll
;                     for (int kt = 0; kt < 4; ++kt)
; #pragma unroll
;                         for (int ks = 0; ks < 2; ++ks) kfr[kt][ks] = *(const bf16x8*)(Ks + (kt * 16 + l15) * KROW + ks * 32 + g * 8);
;                     uint2 vfa[8][2], vfb[8][2];
; #pragma unroll
;                     for (int e = 0; e < 8; ++e)
; #pragma unroll
;                         for (int k2 = 0; k2 < 2; ++k2) { const u16* vp = Vt + (e * 16 + l15) * VROW + k2 * 32 + g * 4; vfa[e][k2] = *(const uint2*)vp; vfb[e][k2] = *(const uint2*)(vp + 16); }
;                     __builtin_amdgcn_sched_barrier(0);
; #pragma unroll
;                     for (int kt = 0; kt < 4; ++kt) { st[kt] = (f32x4){0.f, 0.f, 0.f, 0.f};
; #pragma unroll
;                         for (int ks = 0; ks < 2; ++ks) st[kt] = __builtin_amdgcn_mfma_f32_16x16x32_bf16(kfr[kt][ks], qf[ks], st[kt], 0, 0, 0); }
;     ...
;                     const float mnew = fmaxf(mrun, mloc), alpha = __builtin_amdgcn_exp2f(mrun - mnew);
;                     mrun = mnew;
;                     float psum = 0.f;
; #pragma unroll
;                     for (int kt = 0; kt < 4; ++kt)
; #pragma unroll
;                         for (int jj = 0; jj < 4; ++jj) { const float p = __builtin_amdgcn_exp2f(st[kt][jj] - mnew); st[kt][jj] = p; psum += p; }
;                     lrun = lrun * alpha + psum;
; #pragma unroll
;                     for (int e = 0; e < 8; ++e) ot[e] *= alpha;
;                     bf16x8 pb[2];
; #pragma unroll
;                     for (int k2 = 0; k2 < 2; ++k2) { uint4 pk; pk.x = cvt_pk_bf16(st[2 * k2][0], st[2 * k2][1]); pk.y = cvt_pk_bf16(st[2 * k2][2], st[2 * k2][3]);
;                         pk.z = cvt_pk_bf16(st[2 * k2 + 1][0], st[2 * k2 + 1][1]); pk.w = cvt_pk_bf16(st[2 * k2 + 1][2], st[2 * k2 + 1][3]);
;                         pb[k2] = as_bf16x8(pk); }
; #pragma unroll
;                     for (int e = 0; e < 8; ++e)
; #pragma unroll
;                         for (int k2 = 0; k2 < 2; ++k2) { const uint2 v0 = vfa[e][k2], v1 = vfb[e][k2];
;                             uint4 vv; vv.x = v0.x; vv.y = v0.y; vv.z = v1.x; vv.w = v1.y;
;                             ot[e] = __builtin_amdgcn_mfma_f32_16x16x32_bf16(as_bf16x8(vv), pb[k2], ot[e], 0, 0, 0); }
.Lat_comm0:
	v_exp_f32_e32 v150, v150
	v_exp_f32_e32 v151, v151
	v_exp_f32_e32 v152, v152
	v_exp_f32_e32 v153, v153
	v_exp_f32_e32 v146, v146
	v_exp_f32_e32 v147, v147
	v_exp_f32_e32 v148, v148
	v_exp_f32_e32 v149, v149
	v_cvt_pk_bf16_f32 v220, v150, v151
	v_cvt_pk_bf16_f32 v221, v152, v153
	v_cvt_pk_bf16_f32 v222, v146, v147
	v_cvt_pk_bf16_f32 v223, v148, v149
	s_waitcnt lgkmcnt(8)
	s_nop 0
	v_mfma_f32_16x16x32_bf16 v[58:61], v[134:137], v[220:223], v[58:61]
	v_exp_f32_e32 v138, v138
	v_mfma_f32_16x16x32_bf16 v[50:53], v[126:129], v[220:223], v[50:53]
	v_exp_f32_e32 v139, v139
	v_mfma_f32_16x16x32_bf16 v[42:45], v[118:121], v[220:223], v[42:45]
	v_exp_f32_e32 v140, v140
	v_mfma_f32_16x16x32_bf16 v[46:49], v[110:113], v[220:223], v[46:49]
	v_exp_f32_e32 v141, v141
	v_mfma_f32_16x16x32_bf16 v[54:57], v[102:105], v[220:223], v[54:57]
	v_exp_f32_e32 v142, v142
	v_mfma_f32_16x16x32_bf16 v[62:65], v[94:97], v[220:223], v[62:65]
	v_exp_f32_e32 v143, v143
	v_mfma_f32_16x16x32_bf16 v[66:69], v[86:89], v[220:223], v[66:69]
	v_exp_f32_e32 v144, v144
	v_mfma_f32_16x16x32_bf16 v[70:73], v[78:81], v[220:223], v[70:73]
	v_exp_f32_e32 v145, v145
	v_cvt_pk_bf16_f32 v224, v138, v139
	v_cvt_pk_bf16_f32 v225, v140, v141
	v_cvt_pk_bf16_f32 v226, v142, v143
	v_cvt_pk_bf16_f32 v227, v144, v145
	v_add_f32_e32 v187, v150, v151
	v_add_f32_e32 v187, v152, v187
	v_mfma_f32_16x16x32_bf16 v[58:61], v[130:133], v[224:227], v[58:61]
	v_add_f32_e32 v187, v153, v187
	v_add_f32_e32 v187, v146, v187
	v_mfma_f32_16x16x32_bf16 v[50:53], v[122:125], v[224:227], v[50:53]
	v_add_f32_e32 v187, v147, v187
	v_add_f32_e32 v187, v148, v187
	v_mfma_f32_16x16x32_bf16 v[42:45], v[114:117], v[224:227], v[42:45]
	v_add_f32_e32 v187, v149, v187
	v_add_f32_e32 v187, v138, v187
	v_mfma_f32_16x16x32_bf16 v[46:49], v[106:109], v[224:227], v[46:49]
	v_add_f32_e32 v187, v139, v187
	v_add_f32_e32 v187, v140, v187
	v_mfma_f32_16x16x32_bf16 v[54:57], v[98:101], v[224:227], v[54:57]
	v_add_f32_e32 v187, v141, v187
	v_add_f32_e32 v187, v142, v187
	v_mfma_f32_16x16x32_bf16 v[62:65], v[90:93], v[224:227], v[62:65]
	v_add_f32_e32 v187, v143, v187
	v_add_f32_e32 v187, v144, v187
	v_mfma_f32_16x16x32_bf16 v[66:69], v[82:85], v[224:227], v[66:69]
	v_add_f32_e32 v187, v145, v187
	v_mfma_f32_16x16x32_bf16 v[70:73], v[74:77], v[224:227], v[70:73]
	v_add_f32_e32 v171, v171, v187
	s_cmp_ge_u32 s52, s58
	s_cbranch_scc1 .LBB0_2655
.LBB0_2659:
	ds_read_b128 v[134:137], v205
	ds_read_b128 v[130:133], v204
	ds_read_b128 v[126:129], v205 offset:4096
	ds_read_b128 v[122:125], v204 offset:4096
	ds_read_b128 v[118:121], v205 offset:8192
	ds_read_b128 v[114:117], v204 offset:8192
	ds_read_b128 v[110:113], v205 offset:12288
	ds_read_b128 v[106:109], v204 offset:12288
	ds_read_b128 v[102:105], v205 offset:16384
	ds_read_b128 v[98:101], v204 offset:16384
	ds_read_b128 v[94:97], v205 offset:20480
	ds_read_b128 v[90:93], v204 offset:20480
	ds_read_b128 v[86:89], v205 offset:24576
	ds_read_b128 v[82:85], v204 offset:24576
	ds_read_b128 v[78:81], v205 offset:28672
	ds_read_b128 v[74:77], v204 offset:28672
	s_waitcnt lgkmcnt(14)
	v_mfma_f32_16x16x32_bf16 v[138:141], v[0:3], v[18:21], v[248:251]
	s_cmp_lg_u32 s64, s52
	v_mfma_f32_16x16x32_bf16 v[150:153], v[6:9], v[22:25], v[138:141]
	v_mfma_f32_16x16x32_bf16 v[138:141], v[10:13], v[18:21], v[248:251]
	v_mfma_f32_16x16x32_bf16 v[146:149], v[14:17], v[22:25], v[138:141]
	v_mfma_f32_16x16x32_bf16 v[138:141], v[26:29], v[18:21], v[248:251]
	v_mfma_f32_16x16x32_bf16 v[142:145], v[34:37], v[18:21], v[248:251]
	v_mfma_f32_16x16x32_bf16 v[138:141], v[30:33], v[22:25], v[138:141]
	v_mfma_f32_16x16x32_bf16 v[142:145], v[38:41], v[22:25], v[142:145]
	s_cbranch_scc1 .LBB0_2661
	s_nop 0
	v_cndmask_b32_e64 v173, v150, v241, s[8:9]
	v_cndmask_b32_e64 v150, v173, v150, s[10:11]
	v_cndmask_b32_e64 v151, v241, v151, s[10:11]
	v_cndmask_b32_e64 v152, v152, v241, s[12:13]
	v_cndmask_b32_e64 v153, v153, v241, s[14:15]
	v_cndmask_b32_e64 v146, v146, v241, s[16:17]
	v_cndmask_b32_e64 v147, v147, v241, s[18:19]
	v_cndmask_b32_e64 v148, v148, v241, s[20:21]
	v_cndmask_b32_e64 v149, v149, v241, s[22:23]
	v_cndmask_b32_e64 v138, v138, v241, s[24:25]
	v_cndmask_b32_e64 v139, v139, v241, s[26:27]
	v_cndmask_b32_e64 v140, v140, v241, s[28:29]
	v_cndmask_b32_e64 v141, v141, v241, s[30:31]
	v_cndmask_b32_e64 v142, v142, v241, s[34:35]
	v_cndmask_b32_e64 v143, v143, v241, s[36:37]
	v_cndmask_b32_e64 v144, v144, v241, s[38:39]
	v_cndmask_b32_e64 v145, v145, v241, s[40:41]
